# GEMM accumulator clears use one 64-bit move per register pair (251 fewer VALU per tile unit set)
# speedup vs baseline: 1.0042x; 1.0042x over previous
; template <class Epi, class Sched, bool ALIGN_EPI = false, bool SP2 = false>
; __device__ __forceinline__ void gemm_phase(PG8_LAS unsigned char* lds, const Gemm g, const Sched& S, const Epi& E) {
;     ...
; #pragma unroll
;         for (int a = 0; a < 2; ++a)
; #pragma unroll
;             for (int b = 0; b < 2; ++b)
; #pragma unroll
;                 for (int m = 0; m < 4; ++m)
; #pragma unroll
;                     for (int n = 0; n < 2; ++n) acc[a][b][m][n] = (f32x4){0.f, 0.f, 0.f, 0.f};
;         cur = nxt; cA = nA; cB = nB; ++ui;
.LBB0_312:
	s_add_u32 s30, s30, 0x80
	s_addc_u32 s31, s31, 0
	s_add_u32 s65, s34, 0x100
	v_mov_b32_e32 v4, 0
	s_addc_u32 s66, s35, 0
	s_mov_b32 s34, 0
	v_mov_b64_e32 v[4:5], 0
	v_mov_b64_e32 v[6:7], 0
	v_mov_b64_e32 v[8:9], 0
	v_mov_b64_e32 v[10:11], 0
	v_mov_b64_e32 v[12:13], 0
	v_mov_b64_e32 v[14:15], 0
	v_mov_b64_e32 v[16:17], 0
	v_mov_b64_e32 v[18:19], 0
	v_mov_b64_e32 v[20:21], 0
	v_mov_b64_e32 v[22:23], 0
	v_mov_b64_e32 v[24:25], 0
	v_mov_b64_e32 v[26:27], 0
	v_mov_b64_e32 v[28:29], 0
	v_mov_b64_e32 v[30:31], 0
	v_mov_b64_e32 v[32:33], 0
	v_mov_b64_e32 v[34:35], 0
	v_mov_b64_e32 v[36:37], 0
	v_mov_b64_e32 v[38:39], 0
	v_mov_b64_e32 v[40:41], 0
	v_mov_b64_e32 v[42:43], 0
	v_mov_b64_e32 v[44:45], 0
	v_mov_b64_e32 v[46:47], 0
	v_mov_b64_e32 v[48:49], 0
	v_mov_b64_e32 v[50:51], 0
	v_mov_b64_e32 v[52:53], 0
	v_mov_b64_e32 v[54:55], 0
	v_mov_b64_e32 v[56:57], 0
	v_mov_b64_e32 v[58:59], 0
	v_mov_b64_e32 v[60:61], 0
	v_mov_b64_e32 v[62:63], 0
	v_mov_b64_e32 v[64:65], 0
	v_mov_b64_e32 v[66:67], 0
	v_mov_b64_e32 v[68:69], 0
	v_mov_b64_e32 v[70:71], 0
	v_mov_b64_e32 v[72:73], 0
	v_mov_b64_e32 v[74:75], 0
	v_mov_b64_e32 v[76:77], 0
	v_mov_b64_e32 v[78:79], 0
	v_mov_b64_e32 v[80:81], 0
	v_mov_b64_e32 v[82:83], 0
	v_mov_b64_e32 v[84:85], 0
	v_mov_b64_e32 v[86:87], 0
	v_mov_b64_e32 v[88:89], 0
	v_mov_b64_e32 v[90:91], 0
	v_mov_b64_e32 v[92:93], 0
	v_mov_b64_e32 v[94:95], 0
	v_mov_b64_e32 v[96:97], 0
	v_mov_b64_e32 v[98:99], 0
	v_mov_b64_e32 v[100:101], 0
	v_mov_b64_e32 v[102:103], 0
	v_mov_b64_e32 v[104:105], 0
	v_mov_b64_e32 v[106:107], 0
	v_mov_b64_e32 v[108:109], 0
	v_mov_b64_e32 v[110:111], 0
	v_mov_b64_e32 v[112:113], 0
	v_mov_b64_e32 v[114:115], 0
	v_mov_b64_e32 v[116:117], 0
	v_mov_b64_e32 v[118:119], 0
	v_mov_b64_e32 v[120:121], 0
	v_mov_b64_e32 v[122:123], 0
	v_mov_b64_e32 v[124:125], 0
	v_mov_b64_e32 v[126:127], 0
	v_mov_b64_e32 v[128:129], 0
	v_mov_b64_e32 v[130:131], 0

; #define PG8_STAGE(bufoff, gbase, voff) do { _Pragma("unroll") for (int _i = 0; _i < 2; ++_i) \
;         __builtin_amdgcn_global_load_lds((const unsigned*)((const char*)(gbase) + (voff)[_i]), (PG8_LAS unsigned*)(lds + (bufoff) + ldsw + _i * 8192), 16, 0, 0); } while (0)
; #define PG8_WAIT_V(n) asm volatile("s_waitcnt vmcnt(" #n ")" ::: "memory")
; #define PG8_BAR __builtin_amdgcn_s_barrier()
; __device__ __forceinline__ int bid_() { int t = blockIdx.x; asm volatile("" : "+s"(t)); return t; }
; template <class Epi, class Sched, bool ALIGN_EPI = false, bool SP2 = false>
; __device__ __forceinline__ void gemm_phase(PG8_LAS unsigned char* lds, const Gemm g, const Sched& S, const Epi& E) {
;     ...
;         PG8_STAGE(PG8_SB(1, 0), cB + kstep, voffB); PG8_STAGE(PG8_SA(1, 0), cA + kstep, voffA); PG8_STAGE(PG8_SB(1, 1), cB + hstep + kstep, voffB);
;         PG8_WAIT_V(6); PG8_BAR;
;     } else {
;         PG8_STAGE(PG8_SB(0, 0), cB, voffB); PG8_STAGE(PG8_SA(0, 0), cA, voffA); PG8_STAGE(PG8_SB(0, 1), cB + hstep, voffB); PG8_STAGE(PG8_SA(0, 1), cA + hstep, voffA);
;         if (wr == 1) PG8_BAR;
;         PG8_WAIT_V(4); PG8_BAR;
;         PG8_STAGE(PG8_SB(1, 0), cB + kstep, voffB); PG8_STAGE(PG8_SA(1, 0), cA + kstep, voffA); PG8_STAGE(PG8_SB(1, 1), cB + hstep + kstep, voffB);
;         PG8_WAIT_V(6); PG8_BAR;
; __global__ void __launch_bounds__(512, 2) mk_fwd(Params Pkarg) {
;     ...
;                     for (int c = bid_(); c < 256; c += (int)gridDim.x) {
;                         const int u = c >> 3, ks = c & 7, nt2 = K >> 7;
;                         const int kt0 = 2 * ((ks * nt2) >> 3), kt1 = 2 * (((ks + 1) * nt2) >> 3);
;                         pg8::Gemm g{A + kt0 * 64, Bt + kt0 * 64, MALL, N, (kt1 - kt0) * 64, K};
;                         pg8::Order2 S; S.so.init(MALL, N, 1, 0); S.one = 1; S.valid = 1; S.u1.pm = 32 + (u >> 3); S.u1.pn = u & 7;
.LBB0_330:
	v_lshl_add_u64 v[12:13], s[6:7], 0, v[2:3]
	v_mov_b32_e32 v139, v3
	v_lshl_add_u64 v[14:15], s[6:7], 0, v[138:139]
	v_mov_b32_e32 v1, v3
	s_add_i32 m0, s31, 0x18000
	v_lshl_add_u64 v[12:13], v[12:13], 0, s[84:85]
	v_lshl_add_u64 v[20:21], s[8:9], 0, v[0:1]
	v_mov_b32_e32 v137, v3
	s_waitcnt vmcnt(2)
	s_barrier
	global_load_lds_dwordx4 v[12:13], off
	v_lshl_add_u64 v[12:13], v[14:15], 0, s[84:85]
	s_add_i32 m0, s31, 0x1a000
	s_add_i32 s42, s31, 0x8000
	v_lshl_add_u64 v[22:23], s[8:9], 0, v[136:137]
	global_load_lds_dwordx4 v[12:13], off
	v_lshl_add_u64 v[12:13], v[20:21], 0, s[84:85]
	s_mov_b32 m0, s42
	s_add_i32 s43, s31, 0xa000
	v_lshl_add_u64 v[16:17], s[16:17], 0, v[2:3]
	global_load_lds_dwordx4 v[12:13], off
	v_lshl_add_u64 v[12:13], v[22:23], 0, s[84:85]
	s_mov_b32 m0, s43
	v_lshl_add_u64 v[18:19], s[16:17], 0, v[138:139]
	global_load_lds_dwordx4 v[12:13], off
	s_add_i32 m0, s31, 0x1c000
	v_lshl_add_u64 v[12:13], v[16:17], 0, s[84:85]
	global_load_lds_dwordx4 v[12:13], off
	v_lshl_add_u64 v[12:13], v[18:19], 0, s[84:85]
	s_add_i32 m0, s31, 0x1e000
	s_add_i32 s19, s19, s21
	global_load_lds_dwordx4 v[12:13], off
	s_lshr_b32 s16, s19, 2
	s_and_b32 s16, s16, 0xfe
	s_sub_i32 s41, s16, s18
	s_lshl_b32 s16, s29, 5
	s_waitcnt vmcnt(6)
	v_and_b32_e32 v11, 15, v10
	v_lshrrev_b32_e32 v10, 1, v10
	s_and_b32 s29, s16, 0x60
	v_lshl_or_b32 v135, s13, 6, v11
	v_and_b32_e32 v132, 24, v10
	s_cmp_lt_i32 s41, 1
	s_barrier
	s_cbranch_scc1 .LBB0_334
	s_and_b32 s16, s20, 7
	s_mul_i32 s17, s21, s16
	s_add_i32 s16, s16, 1
	s_mul_i32 s16, s21, s16
	s_lshr_b32 s17, s17, 3
	s_lshr_b32 s16, s16, 2
	s_lshl_b32 s18, s17, 8
	s_and_b32 s16, s16, 0xfe
	s_lshl_b32 s17, s17, 1
	s_sub_i32 s44, s16, s17
	v_lshlrev_b32_e32 v10, 6, v135
	v_lshlrev_b32_e32 v12, 1, v132
	s_movk_i32 s16, 0x3c0
	v_lshlrev_b32_e32 v13, 2, v135
	v_and_or_b32 v10, v10, s16, v12
	s_lshl_b32 s13, s13, 13
	v_and_b32_e32 v13, 32, v13
	v_lshl_or_b32 v12, v11, 6, v12
	v_lshlrev_b32_e32 v11, 2, v11
	v_bitop3_b32 v10, v10, s13, v13 bitop3:0xde
	s_lshl_b32 s13, s29, 7
	v_and_b32_e32 v11, 32, v11
	v_bitop3_b32 v144, v12, s13, v11 bitop3:0xde
	s_ashr_i32 s13, s12, 31
	s_add_i32 s44, s44, -2
	s_lshl_b64 s[12:13], s[12:13], 9
	s_add_u32 s12, s12, 0x4100
	s_addc_u32 s13, s13, 0
	s_mul_i32 s13, s79, s13
	s_mul_hi_u32 s16, s79, s12
	s_add_i32 s16, s16, s13
	s_mul_i32 s12, s79, s12
	s_add_u32 s12, s12, s18
	s_addc_u32 s13, s16, 0
	v_add_u32_e32 v4, v6, v4
	s_add_u32 s12, s22, s12
	v_add_lshl_u32 v4, v4, v5, 1
	v_mov_b32_e32 v5, v3
	s_addc_u32 s13, s23, s13
	v_lshl_add_u64 v[140:141], s[12:13], 0, v[4:5]
	v_add_u32_e32 v4, v9, v7
	v_add_lshl_u32 v4, v4, v8, 1
	v_lshl_add_u64 v[142:143], s[12:13], 0, v[4:5]
	v_mov_b32_e32 v4, 0
	s_mov_b32 s18, 0
	s_mov_b64 s[12:13], 0
	v_add_u32_e32 v145, 0, v10
	v_mov_b64_e32 v[4:5], 0
	v_mov_b64_e32 v[6:7], 0
	v_mov_b64_e32 v[8:9], 0
	v_mov_b64_e32 v[10:11], 0
	v_mov_b64_e32 v[12:13], 0
	v_mov_b64_e32 v[14:15], 0
	v_mov_b64_e32 v[16:17], 0
	v_mov_b64_e32 v[18:19], 0
	v_mov_b64_e32 v[20:21], 0
	v_mov_b64_e32 v[22:23], 0
	v_mov_b64_e32 v[24:25], 0
	v_mov_b64_e32 v[26:27], 0
	v_mov_b64_e32 v[28:29], 0
	v_mov_b64_e32 v[30:31], 0
	v_mov_b64_e32 v[32:33], 0
	v_mov_b64_e32 v[34:35], 0
	v_mov_b64_e32 v[36:37], 0
	v_mov_b64_e32 v[38:39], 0
	v_mov_b64_e32 v[40:41], 0
	v_mov_b64_e32 v[42:43], 0
	v_mov_b64_e32 v[44:45], 0
	v_mov_b64_e32 v[46:47], 0
	v_mov_b64_e32 v[48:49], 0
	v_mov_b64_e32 v[50:51], 0
	v_mov_b64_e32 v[52:53], 0
	v_mov_b64_e32 v[54:55], 0
	v_mov_b64_e32 v[56:57], 0
	v_mov_b64_e32 v[58:59], 0
	v_mov_b64_e32 v[60:61], 0
	v_mov_b64_e32 v[62:63], 0
	v_mov_b64_e32 v[64:65], 0
	v_mov_b64_e32 v[66:67], 0
	v_mov_b64_e32 v[68:69], 0
	v_mov_b64_e32 v[70:71], 0
	v_mov_b64_e32 v[72:73], 0
	v_mov_b64_e32 v[74:75], 0
	v_mov_b64_e32 v[76:77], 0
	v_mov_b64_e32 v[78:79], 0
	v_mov_b64_e32 v[84:85], 0
	v_mov_b64_e32 v[86:87], 0
	v_mov_b64_e32 v[88:89], 0
	v_mov_b64_e32 v[90:91], 0
	v_mov_b64_e32 v[100:101], 0
	v_mov_b64_e32 v[102:103], 0
	v_mov_b64_e32 v[104:105], 0
	v_mov_b64_e32 v[106:107], 0
	v_mov_b64_e32 v[116:117], 0
	v_mov_b64_e32 v[118:119], 0
	v_mov_b64_e32 v[120:121], 0
	v_mov_b64_e32 v[122:123], 0
	s_waitcnt lgkmcnt(0)
	v_mov_b64_e32 v[80:81], 0
	v_mov_b64_e32 v[82:83], 0
	v_mov_b64_e32 v[92:93], 0
	v_mov_b64_e32 v[94:95], 0
	v_mov_b64_e32 v[96:97], 0
	v_mov_b64_e32 v[98:99], 0
	v_mov_b64_e32 v[108:109], 0
	v_mov_b64_e32 v[110:111], 0
	v_mov_b64_e32 v[112:113], 0
	v_mov_b64_e32 v[114:115], 0
	v_mov_b64_e32 v[124:125], 0
	v_mov_b64_e32 v[126:127], 0
	v_mov_b64_e32 v[128:129], 0
	v_mov_b64_e32 v[130:131], 0

; __device__ __forceinline__ int bid_() { int t = blockIdx.x; asm volatile("" : "+s"(t)); return t; }
; template <class Epi, class Sched, bool ALIGN_EPI = false, bool SP2 = false>
; __device__ __forceinline__ void gemm_phase(PG8_LAS unsigned char* lds, const Gemm g, const Sched& S, const Epi& E) {
;     ...
;     f32x4 acc[2][2][4][2];
; #pragma unroll
;     for (int a = 0; a < 2; ++a)
; #pragma unroll
;         for (int b = 0; b < 2; ++b)
; #pragma unroll
;             for (int m = 0; m < 4; ++m)
; #pragma unroll
;                 for (int n = 0; n < 2; ++n) acc[a][b][m][n] = (f32x4){0.f, 0.f, 0.f, 0.f};
; __global__ void __launch_bounds__(512, 2) mk_fwd(Params Pkarg) {
;     ...
;                     for (int c = bid_(); c < 256; c += (int)gridDim.x) {
.LBB0_334:
	v_mov_b32_e32 v131, 0
	v_mov_b32_e32 v83, 0
	v_mov_b64_e32 v[92:93], 0
	v_mov_b64_e32 v[94:95], 0
	v_mov_b64_e32 v[96:97], 0
	v_mov_b64_e32 v[98:99], 0
	v_mov_b64_e32 v[108:109], 0
	v_mov_b64_e32 v[110:111], 0
	v_mov_b64_e32 v[112:113], 0
	v_mov_b64_e32 v[114:115], 0
	v_mov_b64_e32 v[124:125], 0
	v_mov_b64_e32 v[126:127], 0
	v_mov_b64_e32 v[128:129], 0
	v_mov_b64_e32 v[130:131], 0
	s_waitcnt lgkmcnt(0)
	v_mov_b64_e32 v[4:5], 0
	v_mov_b64_e32 v[6:7], 0
	v_mov_b64_e32 v[8:9], 0
	v_mov_b64_e32 v[10:11], 0
	v_mov_b64_e32 v[12:13], 0
	v_mov_b64_e32 v[14:15], 0
	v_mov_b64_e32 v[16:17], 0
	v_mov_b64_e32 v[18:19], 0
	v_mov_b64_e32 v[20:21], 0
	v_mov_b64_e32 v[22:23], 0
	v_mov_b64_e32 v[24:25], 0
	v_mov_b64_e32 v[26:27], 0
	v_mov_b64_e32 v[28:29], 0
	v_mov_b64_e32 v[30:31], 0
	v_mov_b64_e32 v[32:33], 0
	v_mov_b64_e32 v[34:35], 0
	v_mov_b64_e32 v[36:37], 0
	v_mov_b64_e32 v[38:39], 0
	v_mov_b64_e32 v[40:41], 0
	v_mov_b64_e32 v[42:43], 0
	v_mov_b64_e32 v[44:45], 0
	v_mov_b64_e32 v[46:47], 0
	v_mov_b64_e32 v[48:49], 0
	v_mov_b64_e32 v[50:51], 0
	v_mov_b64_e32 v[52:53], 0
	v_mov_b64_e32 v[54:55], 0
	v_mov_b64_e32 v[56:57], 0
	v_mov_b64_e32 v[58:59], 0
	v_mov_b64_e32 v[60:61], 0
	v_mov_b64_e32 v[62:63], 0
	v_mov_b64_e32 v[64:65], 0
	v_mov_b64_e32 v[66:67], 0
	v_mov_b64_e32 v[68:69], 0
	v_mov_b64_e32 v[70:71], 0
	v_mov_b64_e32 v[72:73], 0
	v_mov_b64_e32 v[74:75], 0
	v_mov_b64_e32 v[76:77], 0
	v_mov_b64_e32 v[78:79], 0
	v_mov_b64_e32 v[80:81], 0
	v_mov_b32_e32 v82, 0
	v_mov_b64_e32 v[84:85], 0
	v_mov_b64_e32 v[86:87], 0
	v_mov_b64_e32 v[88:89], 0
	v_mov_b64_e32 v[90:91], 0
	v_mov_b64_e32 v[100:101], 0
	v_mov_b64_e32 v[102:103], 0
	v_mov_b64_e32 v[104:105], 0
	v_mov_b64_e32 v[106:107], 0
	v_mov_b64_e32 v[116:117], 0
	v_mov_b64_e32 v[118:119], 0
	v_mov_b64_e32 v[120:121], 0
	v_mov_b64_e32 v[122:123], 0
	s_cmpk_lt_u32 s28, 0x100
	s_cbranch_scc0 .LBB0_327

;     __device__ bool next(int i, Unit& u) const { if (one) { if (i > 0 || !valid) return false; u = u1; return true; } return so.next(i, u); }
; template <class Epi, class Sched, bool ALIGN_EPI = false, bool SP2 = false>
; __device__ __forceinline__ void gemm_phase(PG8_LAS unsigned char* lds, const Gemm g, const Sched& S, const Epi& E) {
;     ...
;         const bool has_next = S.next(ui + 1, nxt);
;         const char* nA = has_next ? (const char*)g.A + (size_t)nxt.pm * tstep : cA; const char* nB = has_next ? (const char*)g.Bt + (size_t)nxt.pn * tstep : cB;
;     ...
; #pragma unroll
;         for (int a = 0; a < 2; ++a)
; #pragma unroll
;             for (int b = 0; b < 2; ++b)
; #pragma unroll
;                 for (int m = 0; m < 4; ++m)
; #pragma unroll
;                     for (int n = 0; n < 2; ++n) acc[a][b][m][n] = (f32x4){0.f, 0.f, 0.f, 0.f};
.LBB0_352:
	s_ashr_i32 s13, s12, 31
	s_lshl_b64 s[14:15], s[12:13], 20
	s_add_u32 s14, s28, s14
	s_addc_u32 s15, s29, s15
	s_and_b64 s[16:17], s[6:7], exec
	s_cselect_b32 s13, s15, s21
	s_cselect_b32 s47, s14, s20
	s_ashr_i32 s11, s10, 31
	s_lshl_b64 s[16:17], s[10:11], 20
	s_add_u32 s16, s30, s16
	s_addc_u32 s17, s31, s17
	s_and_b64 s[24:25], s[6:7], exec
	s_cselect_b32 s11, s17, s23
	s_cselect_b32 s48, s16, s22
	s_add_u32 s20, s20, 0x80080
	s_addc_u32 s21, s21, 0
	s_add_u32 s49, s22, 0x100
	v_mov_b32_e32 v4, 0
	s_addc_u32 s50, s23, 0
	s_mov_b32 s51, -2
	v_mov_b64_e32 v[4:5], 0
	v_mov_b64_e32 v[6:7], 0
	v_mov_b64_e32 v[8:9], 0
	v_mov_b64_e32 v[10:11], 0
	v_mov_b64_e32 v[12:13], 0
	v_mov_b64_e32 v[14:15], 0
	v_mov_b64_e32 v[16:17], 0
	v_mov_b64_e32 v[18:19], 0
	v_mov_b64_e32 v[20:21], 0
	v_mov_b64_e32 v[22:23], 0
	v_mov_b64_e32 v[24:25], 0
	v_mov_b64_e32 v[26:27], 0
	v_mov_b64_e32 v[28:29], 0
	v_mov_b64_e32 v[30:31], 0
	v_mov_b64_e32 v[32:33], 0
	v_mov_b64_e32 v[34:35], 0
	v_mov_b64_e32 v[36:37], 0
	v_mov_b64_e32 v[38:39], 0
	v_mov_b64_e32 v[40:41], 0
	v_mov_b64_e32 v[42:43], 0
	v_mov_b64_e32 v[44:45], 0
	v_mov_b64_e32 v[46:47], 0
	v_mov_b64_e32 v[48:49], 0
	v_mov_b64_e32 v[50:51], 0
	v_mov_b64_e32 v[52:53], 0
	v_mov_b64_e32 v[54:55], 0
	v_mov_b64_e32 v[56:57], 0
	v_mov_b64_e32 v[58:59], 0
	v_mov_b64_e32 v[60:61], 0
	v_mov_b64_e32 v[62:63], 0
	v_mov_b64_e32 v[64:65], 0
	v_mov_b64_e32 v[66:67], 0
	v_mov_b64_e32 v[68:69], 0
	v_mov_b64_e32 v[70:71], 0
	v_mov_b64_e32 v[72:73], 0
	v_mov_b64_e32 v[74:75], 0
	v_mov_b64_e32 v[76:77], 0
	v_mov_b64_e32 v[78:79], 0
	v_mov_b64_e32 v[80:81], 0
	v_mov_b64_e32 v[82:83], 0
	v_mov_b64_e32 v[84:85], 0
	v_mov_b64_e32 v[86:87], 0
	v_mov_b64_e32 v[88:89], 0
	v_mov_b64_e32 v[90:91], 0
	v_mov_b64_e32 v[92:93], 0
	v_mov_b64_e32 v[94:95], 0
	v_mov_b64_e32 v[96:97], 0
	v_mov_b64_e32 v[98:99], 0
	v_mov_b64_e32 v[100:101], 0
	v_mov_b64_e32 v[102:103], 0
	v_mov_b64_e32 v[104:105], 0
	v_mov_b64_e32 v[106:107], 0
	v_mov_b64_e32 v[108:109], 0
	v_mov_b64_e32 v[110:111], 0
	v_mov_b64_e32 v[112:113], 0
	v_mov_b64_e32 v[114:115], 0
	v_mov_b64_e32 v[116:117], 0
	v_mov_b64_e32 v[118:119], 0
	v_mov_b64_e32 v[120:121], 0
	v_mov_b64_e32 v[122:123], 0
	v_mov_b64_e32 v[124:125], 0
	v_mov_b64_e32 v[126:127], 0
	v_mov_b64_e32 v[128:129], 0
	v_mov_b64_e32 v[130:131], 0
